# v91 + dense QKV epilogue: QK-norm squares as scalar multiplies instead of same-source packed multiplies
# speedup vs baseline: 1.0186x; 1.0081x over previous
.LBB0_773:
	s_lshl_b32 s4, s4, 10
	s_add_i32 s4, s4, 0
	s_lshl_b32 s6, s7, 8
	s_add_i32 s97, s4, s6
	s_add_i32 s97, s97, 0x20000
	v_mov_b32_e32 v179, v175
	v_mov_b32_e32 v157, v135
	v_lshl_add_u32 v156, v179, 2, s97
	ds_read_b32 v170, v156
	v_mov_b32_e32 v135, v131
	s_lshl_b32 s94, s7, 6
	s_lshl_b32 s66, s5, 8
	v_mov_b32_e32 v156, v130
	s_waitcnt lgkmcnt(0)
	v_pk_mul_f32 v[168:169], v[134:135], v[170:171] op_sel_hi:[1,0]
	v_mov_b32_e32 v134, v132
	v_mov_b32_e32 v135, v137
	v_pk_mul_f32 v[162:163], v[134:135], v[170:171] op_sel_hi:[1,0]
	v_mov_b32_e32 v135, v127
	v_mov_b32_e32 v127, v123
	v_mov_b32_e32 v137, v133
	v_pk_mul_f32 v[160:161], v[126:127], v[170:171] op_sel_hi:[1,0]
	v_mov_b32_e32 v126, v124
	v_mov_b32_e32 v127, v129
	v_mov_b32_e32 v129, v125
	s_add_i32 s4, s94, s66
	v_pk_mul_f32 v[166:167], v[156:157], v[170:171] op_sel_hi:[1,0]
	v_pk_mul_f32 v[164:165], v[136:137], v[170:171] op_sel_hi:[1,0]
	v_mov_b32_e32 v134, v122
	v_pk_mul_f32 v[136:137], v[126:127], v[170:171] op_sel_hi:[1,0]
	v_pk_mul_f32 v[156:157], v[128:129], v[170:171] op_sel_hi:[1,0]
	v_cndmask_b32_e64 v126, 0, 1, s[82:83]
	v_lshlrev_b32_e32 v177, 2, v178
	v_add_u32_e32 v180, s4, v179
	v_pk_mul_f32 v[158:159], v[134:135], v[170:171] op_sel_hi:[1,0]
	v_cmp_ne_u32_e64 s[40:41], 1, v126
	s_andn2_b64 vcc, exec, s[82:83]
	v_pk_mov_b32 v[134:135], v[136:137], v[156:157] op_sel:[1,0]
	s_cbranch_vccnz .LBB0_775
	v_mul_f32_e32 v122, v168, v168
	v_mul_f32_e32 v123, v169, v169
	v_mul_f32_e32 v124, v166, v166
	v_mul_f32_e32 v125, v167, v167
	v_mul_f32_e32 v126, v164, v164
	v_mul_f32_e32 v127, v165, v165
	v_add_f32_e32 v122, v122, v125
	v_mul_f32_e32 v128, v162, v162
	v_mul_f32_e32 v129, v163, v163
	v_add_f32_e32 v122, v126, v122
	v_add_f32_e32 v122, v129, v122
	v_add_f32_e32 v122, v124, v122
	v_add_f32_e32 v122, v123, v122
	v_add_f32_e32 v122, v128, v122
	v_add_f32_e32 v122, v127, v122
	v_fmac_f32_e32 v122, v160, v160
	v_mul_f32_e32 v130, v134, v134
	v_mul_f32_e32 v131, v135, v135
	v_fmac_f32_e32 v122, v159, v159
	v_pk_mov_b32 v[132:133], v[160:161], v[158:159] op_sel:[1,0]
	v_add_f32_e32 v122, v131, v122
	v_mul_f32_e32 v132, v132, v132
	v_mul_f32_e32 v133, v133, v133
	v_add_f32_e32 v122, v130, v122
	v_and_b32_e32 v124, 64, v238
	v_pk_mov_b32 v[134:135], v[156:157], v[136:137] op_sel:[1,0]
	v_add_f32_e32 v122, v133, v122
	v_xor_b32_e32 v123, 16, v238
	v_add_u32_e32 v124, 64, v124
	v_mul_f32_e32 v134, v134, v134
	v_mul_f32_e32 v135, v135, v135
	v_add_f32_e32 v122, v132, v122
	v_cmp_lt_i32_e32 vcc, v123, v124
	v_add_f32_e32 v122, v135, v122
	v_add_f32_e32 v122, v134, v122
	v_cndmask_b32_e32 v123, v238, v123, vcc
	v_lshlrev_b32_e32 v123, 2, v123
	v_mov_b32_e32 v123, v122
	s_nop 1
	v_permlane16_swap_b32 v123, v122
	v_readlane_b32 s5, v253, 18
	s_waitcnt lgkmcnt(0)
	v_add_f32_e32 v122, v122, v123
	v_xor_b32_e32 v123, 32, v238
	v_cmp_lt_i32_e32 vcc, v123, v124
	s_nop 1
	v_cndmask_b32_e32 v123, v238, v123, vcc
	v_lshlrev_b32_e32 v123, 2, v123
	v_mov_b32_e32 v123, v122
	s_nop 1
	v_permlane32_swap_b32 v123, v122
	s_waitcnt lgkmcnt(0)
	v_add_f32_e32 v122, v122, v123
	v_fmamk_f32 v122, v122, 0x3c800000, v236
	v_rsq_f32_e32 v134, v122
	v_lshrrev_b32_e32 v122, 2, v180
	v_and_b32_e32 v122, 0x3f0, v122
	v_add_u32_e32 v122, v122, v177
	v_lshl_add_u32 v126, v122, 3, s5
	ds_read_b128 v[122:125], v126
	ds_read_b128 v[128:131], v126 offset:16
	v_pk_mul_f32 v[126:127], v[54:55], v[134:135] op_sel_hi:[1,0]
	v_pk_mul_f32 v[132:133], v[154:155], v[134:135] op_sel_hi:[1,0]
	v_pk_mul_f32 v[126:127], v[166:167], v[126:127]
	v_pk_mul_f32 v[132:133], v[168:169], v[132:133]
	s_waitcnt lgkmcnt(0)
	v_mov_b32_e32 v167, v124
	v_mov_b32_e32 v168, v122
	v_mov_b32_e32 v169, v125
	v_mov_b32_e32 v182, v124
	v_mov_b32_e32 v183, v122
	v_mov_b32_e32 v122, v125
	v_pk_mov_b32 v[124:125], v[132:133], v[126:127] op_sel:[1,0]
	v_mov_b32_e32 v166, v123
	v_pk_mul_f32 v[168:169], v[168:169], v[126:127]
	v_pk_mul_f32 v[122:123], v[122:123], v[124:125]
	v_pk_mul_f32 v[124:125], v[56:57], v[134:135] op_sel_hi:[1,0]
	v_pk_mov_b32 v[184:185], v[126:127], v[132:133] op_sel:[1,0]
	v_pk_fma_f32 v[126:127], v[166:167], v[132:133], v[168:169]
	v_pk_mul_f32 v[124:125], v[162:163], v[124:125]
	v_mov_b32_e32 v163, v130
	v_mov_b32_e32 v166, v130
	v_lshlrev_b32_e32 v130, 4, v179
	v_pk_mul_f32 v[132:133], v[152:153], v[134:135] op_sel_hi:[1,0]
	v_and_b32_e32 v130, 0x3f0, v130
	v_pk_mul_f32 v[132:133], v[164:165], v[132:133]
	v_mov_b32_e32 v164, v128
	v_mov_b32_e32 v165, v131
	v_add_u32_e32 v130, v130, v177
	v_mov_b32_e32 v162, v129
	v_pk_mul_f32 v[164:165], v[164:165], v[124:125]
	v_mov_b32_e32 v167, v128
	v_pk_mov_b32 v[168:169], v[124:125], v[132:133] op_sel:[1,0]
	v_mov_b32_e32 v128, v131
	v_pk_mov_b32 v[124:125], v[132:133], v[124:125] op_sel:[1,0]
	v_lshl_add_u32 v135, v130, 3, s5
	v_pk_mul_f32 v[124:125], v[128:129], v[124:125]
	v_pk_fma_f32 v[128:129], v[162:163], v[132:133], v[164:165]
	ds_read_b128 v[130:133], v135
	ds_read_b128 v[162:165], v135 offset:16
	v_pk_fma_f32 v[124:125], v[166:167], v[168:169], v[124:125] neg_lo:[0,0,1] neg_hi:[0,0,1]
	v_pk_mul_f32 v[166:167], v[46:47], v[134:135] op_sel_hi:[1,0]
	v_pk_fma_f32 v[122:123], v[182:183], v[184:185], v[122:123] neg_lo:[0,0,1] neg_hi:[0,0,1]
	v_pk_mul_f32 v[158:159], v[158:159], v[166:167]
	v_pk_mul_f32 v[166:167], v[150:151], v[134:135] op_sel_hi:[1,0]
	s_waitcnt lgkmcnt(0)
	v_mov_b32_e32 v168, v130
	v_pk_mul_f32 v[160:161], v[160:161], v[166:167]
	v_mov_b32_e32 v169, v133
	v_mov_b32_e32 v167, v132
	v_pk_mul_f32 v[168:169], v[168:169], v[158:159]
	v_mov_b32_e32 v182, v132
	v_mov_b32_e32 v183, v130
	v_pk_mov_b32 v[184:185], v[158:159], v[160:161] op_sel:[1,0]
	v_mov_b32_e32 v130, v133
	v_pk_mov_b32 v[132:133], v[160:161], v[158:159] op_sel:[1,0]
	v_pk_mul_f32 v[158:159], v[48:49], v[134:135] op_sel_hi:[1,0]
	v_pk_mul_f32 v[134:135], v[148:149], v[134:135] op_sel_hi:[1,0]
	v_mov_b32_e32 v166, v131
	v_pk_mul_f32 v[130:131], v[130:131], v[132:133]
	v_pk_mul_f32 v[136:137], v[136:137], v[158:159]
	v_pk_mul_f32 v[156:157], v[156:157], v[134:135]
	v_mov_b32_e32 v134, v162
	v_mov_b32_e32 v135, v165
	v_pk_fma_f32 v[132:133], v[182:183], v[184:185], v[130:131] neg_lo:[0,0,1] neg_hi:[0,0,1]
	v_pk_fma_f32 v[130:131], v[166:167], v[160:161], v[168:169]
	v_pk_mul_f32 v[160:161], v[134:135], v[136:137]
	v_mov_b32_e32 v135, v162
	v_pk_mov_b32 v[166:167], v[136:137], v[156:157] op_sel:[1,0]
	v_mov_b32_e32 v162, v165
	v_pk_mov_b32 v[136:137], v[156:157], v[136:137] op_sel:[1,0]
	v_mov_b32_e32 v158, v163
	v_mov_b32_e32 v159, v164
	v_mov_b32_e32 v134, v164
	v_pk_mul_f32 v[136:137], v[162:163], v[136:137]
	s_nop 0
	v_pk_fma_f32 v[134:135], v[134:135], v[166:167], v[136:137] neg_lo:[0,0,1] neg_hi:[0,0,1]
	v_pk_fma_f32 v[136:137], v[158:159], v[156:157], v[160:161]
	v_cndmask_b32_e64 v156, 0, 1, s[44:45]
	v_cmp_ne_u32_e64 s[42:43], 1, v156
	s_andn2_b64 vcc, exec, s[44:45]
	s_cbranch_vccz .LBB0_776
	s_branch .LBB0_777

.LBB0_781:
	v_mov_b32_e32 v137, v175
	s_nop 0
	v_mov_b32_e32 v123, v119
	v_lshl_add_u32 v122, v137, 2, s97
	ds_read_b32 v136, v122 offset:64
	v_mov_b32_e32 v119, v115
	v_mov_b32_e32 v122, v114
	v_add3_u32 v158, v137, s94, 16
	v_add_u32_e32 v157, s66, v158
	s_waitcnt lgkmcnt(0)
	v_pk_mul_f32 v[134:135], v[118:119], v[136:137] op_sel_hi:[1,0]
	v_mov_b32_e32 v118, v116
	v_mov_b32_e32 v119, v121
	v_pk_mul_f32 v[128:129], v[118:119], v[136:137] op_sel_hi:[1,0]
	v_mov_b32_e32 v119, v111
	v_mov_b32_e32 v111, v107
	v_mov_b32_e32 v121, v117
	v_pk_mul_f32 v[126:127], v[110:111], v[136:137] op_sel_hi:[1,0]
	v_mov_b32_e32 v110, v108
	v_mov_b32_e32 v111, v113
	v_mov_b32_e32 v113, v109
	v_pk_mul_f32 v[132:133], v[122:123], v[136:137] op_sel_hi:[1,0]
	v_pk_mul_f32 v[130:131], v[120:121], v[136:137] op_sel_hi:[1,0]
	v_mov_b32_e32 v118, v106
	v_pk_mul_f32 v[120:121], v[110:111], v[136:137] op_sel_hi:[1,0]
	v_pk_mul_f32 v[122:123], v[112:113], v[136:137] op_sel_hi:[1,0]
	v_pk_mul_f32 v[124:125], v[118:119], v[136:137] op_sel_hi:[1,0]
	s_and_b64 vcc, exec, s[40:41]
	v_pk_mov_b32 v[118:119], v[120:121], v[122:123] op_sel:[1,0]
	s_cbranch_vccnz .LBB0_783
	v_mul_f32_e32 v106, v134, v134
	v_mul_f32_e32 v107, v135, v135
	v_mul_f32_e32 v108, v132, v132
	v_mul_f32_e32 v109, v133, v133
	v_mul_f32_e32 v110, v130, v130
	v_mul_f32_e32 v111, v131, v131
	v_add_f32_e32 v106, v106, v109
	v_mul_f32_e32 v112, v128, v128
	v_mul_f32_e32 v113, v129, v129
	v_add_f32_e32 v106, v110, v106
	v_add_f32_e32 v106, v113, v106
	v_add_f32_e32 v106, v108, v106
	v_add_f32_e32 v106, v107, v106
	v_add_f32_e32 v106, v112, v106
	v_add_f32_e32 v106, v111, v106
	v_fmac_f32_e32 v106, v126, v126
	v_mul_f32_e32 v114, v118, v118
	v_mul_f32_e32 v115, v119, v119
	v_fmac_f32_e32 v106, v125, v125
	v_pk_mov_b32 v[116:117], v[126:127], v[124:125] op_sel:[1,0]
	v_add_f32_e32 v106, v115, v106
	v_mul_f32_e32 v116, v116, v116
	v_mul_f32_e32 v117, v117, v117
	v_add_f32_e32 v106, v114, v106
	v_and_b32_e32 v108, 64, v238
	v_pk_mov_b32 v[118:119], v[122:123], v[120:121] op_sel:[1,0]
	v_add_f32_e32 v106, v117, v106
	v_xor_b32_e32 v107, 16, v238
	v_add_u32_e32 v108, 64, v108
	v_mul_f32_e32 v118, v118, v118
	v_mul_f32_e32 v119, v119, v119
	v_add_f32_e32 v106, v116, v106
	v_cmp_lt_i32_e32 vcc, v107, v108
	v_add_f32_e32 v106, v119, v106
	v_add_f32_e32 v106, v118, v106
	v_cndmask_b32_e32 v107, v238, v107, vcc
	v_lshlrev_b32_e32 v107, 2, v107
	v_mov_b32_e32 v107, v106
	s_nop 1
	v_permlane16_swap_b32 v107, v106
	v_readlane_b32 s5, v253, 18
	s_waitcnt lgkmcnt(0)
	v_add_f32_e32 v106, v106, v107
	v_xor_b32_e32 v107, 32, v238
	v_cmp_lt_i32_e32 vcc, v107, v108
	s_nop 1
	v_cndmask_b32_e32 v107, v238, v107, vcc
	v_lshlrev_b32_e32 v107, 2, v107
	v_mov_b32_e32 v107, v106
	s_nop 1
	v_permlane32_swap_b32 v107, v106
	s_waitcnt lgkmcnt(0)
	v_add_f32_e32 v106, v106, v107
	v_fmamk_f32 v106, v106, 0x3c800000, v236
	v_rsq_f32_e32 v118, v106
	v_lshrrev_b32_e32 v106, 2, v157
	v_and_b32_e32 v106, 0x3f0, v106
	v_add_u32_e32 v106, v106, v177
	v_lshl_add_u32 v110, v106, 3, s5
	ds_read_b128 v[106:109], v110
	ds_read_b128 v[112:115], v110 offset:16
	v_pk_mul_f32 v[110:111], v[54:55], v[118:119] op_sel_hi:[1,0]
	v_pk_mul_f32 v[116:117], v[154:155], v[118:119] op_sel_hi:[1,0]
	v_pk_mul_f32 v[110:111], v[132:133], v[110:111]
	v_pk_mul_f32 v[116:117], v[134:135], v[116:117]
	s_waitcnt lgkmcnt(0)
	v_mov_b32_e32 v133, v108
	v_mov_b32_e32 v134, v106
	v_mov_b32_e32 v135, v109
	v_mov_b32_e32 v160, v108
	v_mov_b32_e32 v161, v106
	v_mov_b32_e32 v106, v109
	v_pk_mov_b32 v[108:109], v[116:117], v[110:111] op_sel:[1,0]
	v_mov_b32_e32 v132, v107
	v_pk_mul_f32 v[134:135], v[134:135], v[110:111]
	v_pk_mul_f32 v[106:107], v[106:107], v[108:109]
	v_pk_mul_f32 v[108:109], v[56:57], v[118:119] op_sel_hi:[1,0]
	v_pk_mov_b32 v[162:163], v[110:111], v[116:117] op_sel:[1,0]
	v_pk_fma_f32 v[110:111], v[132:133], v[116:117], v[134:135]
	v_pk_mul_f32 v[108:109], v[128:129], v[108:109]
	v_mov_b32_e32 v129, v114
	v_mov_b32_e32 v132, v114
	v_lshlrev_b32_e32 v114, 4, v158
	v_pk_mul_f32 v[116:117], v[152:153], v[118:119] op_sel_hi:[1,0]
	v_and_b32_e32 v114, 0x3f0, v114
	v_pk_mul_f32 v[116:117], v[130:131], v[116:117]
	v_mov_b32_e32 v130, v112
	v_mov_b32_e32 v131, v115
	v_add_u32_e32 v114, v114, v177
	v_mov_b32_e32 v128, v113
	v_pk_mul_f32 v[130:131], v[130:131], v[108:109]
	v_mov_b32_e32 v133, v112
	v_pk_mov_b32 v[134:135], v[108:109], v[116:117] op_sel:[1,0]
	v_mov_b32_e32 v112, v115
	v_pk_mov_b32 v[108:109], v[116:117], v[108:109] op_sel:[1,0]
	v_lshl_add_u32 v119, v114, 3, s5
	v_pk_mul_f32 v[108:109], v[112:113], v[108:109]
	v_pk_fma_f32 v[112:113], v[128:129], v[116:117], v[130:131]
	ds_read_b128 v[114:117], v119
	ds_read_b128 v[128:131], v119 offset:16
	v_pk_fma_f32 v[108:109], v[132:133], v[134:135], v[108:109] neg_lo:[0,0,1] neg_hi:[0,0,1]
	v_pk_mul_f32 v[132:133], v[46:47], v[118:119] op_sel_hi:[1,0]
	v_pk_fma_f32 v[106:107], v[160:161], v[162:163], v[106:107] neg_lo:[0,0,1] neg_hi:[0,0,1]
	v_pk_mul_f32 v[124:125], v[124:125], v[132:133]
	v_pk_mul_f32 v[132:133], v[150:151], v[118:119] op_sel_hi:[1,0]
	s_waitcnt lgkmcnt(0)
	v_mov_b32_e32 v134, v114
	v_pk_mul_f32 v[126:127], v[126:127], v[132:133]
	v_mov_b32_e32 v135, v117
	v_mov_b32_e32 v133, v116
	v_pk_mul_f32 v[134:135], v[134:135], v[124:125]
	v_mov_b32_e32 v158, v116
	v_mov_b32_e32 v159, v114
	v_pk_mov_b32 v[160:161], v[124:125], v[126:127] op_sel:[1,0]
	v_mov_b32_e32 v114, v117
	v_pk_mov_b32 v[116:117], v[126:127], v[124:125] op_sel:[1,0]
	v_pk_mul_f32 v[124:125], v[48:49], v[118:119] op_sel_hi:[1,0]
	v_pk_mul_f32 v[118:119], v[148:149], v[118:119] op_sel_hi:[1,0]
	v_mov_b32_e32 v132, v115
	v_pk_mul_f32 v[114:115], v[114:115], v[116:117]
	v_pk_mul_f32 v[120:121], v[120:121], v[124:125]
	v_pk_mul_f32 v[122:123], v[122:123], v[118:119]
	v_mov_b32_e32 v118, v128
	v_mov_b32_e32 v119, v131
	v_pk_fma_f32 v[116:117], v[158:159], v[160:161], v[114:115] neg_lo:[0,0,1] neg_hi:[0,0,1]
	v_pk_fma_f32 v[114:115], v[132:133], v[126:127], v[134:135]
	v_pk_mul_f32 v[126:127], v[118:119], v[120:121]
	v_mov_b32_e32 v119, v128
	v_pk_mov_b32 v[132:133], v[120:121], v[122:123] op_sel:[1,0]
	v_mov_b32_e32 v128, v131
	v_pk_mov_b32 v[120:121], v[122:123], v[120:121] op_sel:[1,0]
	v_mov_b32_e32 v124, v129
	v_mov_b32_e32 v125, v130
	v_mov_b32_e32 v118, v130
	v_pk_mul_f32 v[120:121], v[128:129], v[120:121]
	s_nop 0
	v_pk_fma_f32 v[118:119], v[118:119], v[132:133], v[120:121] neg_lo:[0,0,1] neg_hi:[0,0,1]
	v_pk_fma_f32 v[120:121], v[124:125], v[122:123], v[126:127]
	s_and_b64 vcc, exec, s[42:43]
	s_cbranch_vccz .LBB0_784
	s_branch .LBB0_785

.LBB0_789:
	v_mov_b32_e32 v121, v175
	s_nop 0
	v_mov_b32_e32 v107, v103
	v_lshl_add_u32 v106, v121, 2, s97
	ds_read_b32 v120, v106 offset:128
	v_mov_b32_e32 v103, v99
	v_mov_b32_e32 v106, v98
	v_add3_u32 v123, v121, s94, 32
	v_add_u32_e32 v122, s66, v123
	s_waitcnt lgkmcnt(0)
	v_pk_mul_f32 v[118:119], v[102:103], v[120:121] op_sel_hi:[1,0]
	v_mov_b32_e32 v102, v100
	v_mov_b32_e32 v103, v105
	v_pk_mul_f32 v[112:113], v[102:103], v[120:121] op_sel_hi:[1,0]
	v_mov_b32_e32 v103, v95
	v_mov_b32_e32 v95, v91
	v_mov_b32_e32 v105, v101
	v_pk_mul_f32 v[110:111], v[94:95], v[120:121] op_sel_hi:[1,0]
	v_mov_b32_e32 v94, v92
	v_mov_b32_e32 v95, v97
	v_mov_b32_e32 v97, v93
	v_pk_mul_f32 v[116:117], v[106:107], v[120:121] op_sel_hi:[1,0]
	v_pk_mul_f32 v[114:115], v[104:105], v[120:121] op_sel_hi:[1,0]
	v_mov_b32_e32 v102, v90
	v_pk_mul_f32 v[104:105], v[94:95], v[120:121] op_sel_hi:[1,0]
	v_pk_mul_f32 v[106:107], v[96:97], v[120:121] op_sel_hi:[1,0]
	v_pk_mul_f32 v[108:109], v[102:103], v[120:121] op_sel_hi:[1,0]
	s_and_b64 vcc, exec, s[40:41]
	v_pk_mov_b32 v[102:103], v[104:105], v[106:107] op_sel:[1,0]
	s_cbranch_vccnz .LBB0_791
	v_mul_f32_e32 v90, v118, v118
	v_mul_f32_e32 v91, v119, v119
	v_mul_f32_e32 v92, v116, v116
	v_mul_f32_e32 v93, v117, v117
	v_mul_f32_e32 v94, v114, v114
	v_mul_f32_e32 v95, v115, v115
	v_add_f32_e32 v90, v90, v93
	v_mul_f32_e32 v96, v112, v112
	v_mul_f32_e32 v97, v113, v113
	v_add_f32_e32 v90, v94, v90
	v_add_f32_e32 v90, v97, v90
	v_add_f32_e32 v90, v92, v90
	v_add_f32_e32 v90, v91, v90
	v_add_f32_e32 v90, v96, v90
	v_add_f32_e32 v90, v95, v90
	v_fmac_f32_e32 v90, v110, v110
	v_mul_f32_e32 v98, v102, v102
	v_mul_f32_e32 v99, v103, v103
	v_fmac_f32_e32 v90, v109, v109
	v_pk_mov_b32 v[100:101], v[110:111], v[108:109] op_sel:[1,0]
	v_add_f32_e32 v90, v99, v90
	v_mul_f32_e32 v100, v100, v100
	v_mul_f32_e32 v101, v101, v101
	v_add_f32_e32 v90, v98, v90
	v_and_b32_e32 v92, 64, v238
	v_pk_mov_b32 v[102:103], v[106:107], v[104:105] op_sel:[1,0]
	v_add_f32_e32 v90, v101, v90
	v_xor_b32_e32 v91, 16, v238
	v_add_u32_e32 v92, 64, v92
	v_mul_f32_e32 v102, v102, v102
	v_mul_f32_e32 v103, v103, v103
	v_add_f32_e32 v90, v100, v90
	v_cmp_lt_i32_e32 vcc, v91, v92
	v_add_f32_e32 v90, v103, v90
	v_add_f32_e32 v90, v102, v90
	v_cndmask_b32_e32 v91, v238, v91, vcc
	v_lshlrev_b32_e32 v91, 2, v91
	v_mov_b32_e32 v91, v90
	s_nop 1
	v_permlane16_swap_b32 v91, v90
	v_readlane_b32 s5, v253, 18
	s_waitcnt lgkmcnt(0)
	v_add_f32_e32 v90, v90, v91
	v_xor_b32_e32 v91, 32, v238
	v_cmp_lt_i32_e32 vcc, v91, v92
	s_nop 1
	v_cndmask_b32_e32 v91, v238, v91, vcc
	v_lshlrev_b32_e32 v91, 2, v91
	v_mov_b32_e32 v91, v90
	s_nop 1
	v_permlane32_swap_b32 v91, v90
	s_waitcnt lgkmcnt(0)
	v_add_f32_e32 v90, v90, v91
	v_fmamk_f32 v90, v90, 0x3c800000, v236
	v_rsq_f32_e32 v102, v90
	v_lshrrev_b32_e32 v90, 2, v122
	v_and_b32_e32 v90, 0x3f0, v90
	v_add_u32_e32 v90, v90, v177
	v_lshl_add_u32 v94, v90, 3, s5
	ds_read_b128 v[90:93], v94
	ds_read_b128 v[96:99], v94 offset:16
	v_pk_mul_f32 v[94:95], v[54:55], v[102:103] op_sel_hi:[1,0]
	v_pk_mul_f32 v[100:101], v[154:155], v[102:103] op_sel_hi:[1,0]
	v_pk_mul_f32 v[94:95], v[116:117], v[94:95]
	v_pk_mul_f32 v[100:101], v[118:119], v[100:101]
	s_waitcnt lgkmcnt(0)
	v_mov_b32_e32 v117, v92
	v_mov_b32_e32 v118, v90
	v_mov_b32_e32 v119, v93
	v_mov_b32_e32 v124, v92
	v_mov_b32_e32 v125, v90
	v_mov_b32_e32 v90, v93
	v_pk_mov_b32 v[92:93], v[100:101], v[94:95] op_sel:[1,0]
	v_mov_b32_e32 v116, v91
	v_pk_mul_f32 v[118:119], v[118:119], v[94:95]
	v_pk_mul_f32 v[90:91], v[90:91], v[92:93]
	v_pk_mul_f32 v[92:93], v[56:57], v[102:103] op_sel_hi:[1,0]
	v_pk_mov_b32 v[126:127], v[94:95], v[100:101] op_sel:[1,0]
	v_pk_fma_f32 v[94:95], v[116:117], v[100:101], v[118:119]
	v_pk_mul_f32 v[92:93], v[112:113], v[92:93]
	v_mov_b32_e32 v113, v98
	v_mov_b32_e32 v116, v98
	v_lshlrev_b32_e32 v98, 4, v123
	v_pk_mul_f32 v[100:101], v[152:153], v[102:103] op_sel_hi:[1,0]
	v_and_b32_e32 v98, 0x3f0, v98
	v_pk_mul_f32 v[100:101], v[114:115], v[100:101]
	v_mov_b32_e32 v114, v96
	v_mov_b32_e32 v115, v99
	v_add_u32_e32 v98, v98, v177
	v_mov_b32_e32 v112, v97
	v_pk_mul_f32 v[114:115], v[114:115], v[92:93]
	v_mov_b32_e32 v117, v96
	v_pk_mov_b32 v[118:119], v[92:93], v[100:101] op_sel:[1,0]
	v_mov_b32_e32 v96, v99
	v_pk_mov_b32 v[92:93], v[100:101], v[92:93] op_sel:[1,0]
	v_lshl_add_u32 v103, v98, 3, s5
	v_pk_mul_f32 v[92:93], v[96:97], v[92:93]
	v_pk_fma_f32 v[96:97], v[112:113], v[100:101], v[114:115]
	ds_read_b128 v[98:101], v103
	ds_read_b128 v[112:115], v103 offset:16
	v_pk_fma_f32 v[92:93], v[116:117], v[118:119], v[92:93] neg_lo:[0,0,1] neg_hi:[0,0,1]
	v_pk_mul_f32 v[116:117], v[46:47], v[102:103] op_sel_hi:[1,0]
	v_pk_fma_f32 v[90:91], v[124:125], v[126:127], v[90:91] neg_lo:[0,0,1] neg_hi:[0,0,1]
	v_pk_mul_f32 v[108:109], v[108:109], v[116:117]
	v_pk_mul_f32 v[116:117], v[150:151], v[102:103] op_sel_hi:[1,0]
	s_waitcnt lgkmcnt(0)
	v_mov_b32_e32 v118, v98
	v_pk_mul_f32 v[110:111], v[110:111], v[116:117]
	v_mov_b32_e32 v119, v101
	v_mov_b32_e32 v117, v100
	v_pk_mul_f32 v[118:119], v[118:119], v[108:109]
	v_mov_b32_e32 v124, v100
	v_mov_b32_e32 v125, v98
	v_pk_mov_b32 v[126:127], v[108:109], v[110:111] op_sel:[1,0]
	v_mov_b32_e32 v98, v101
	v_pk_mov_b32 v[100:101], v[110:111], v[108:109] op_sel:[1,0]
	v_pk_mul_f32 v[108:109], v[48:49], v[102:103] op_sel_hi:[1,0]
	v_pk_mul_f32 v[102:103], v[148:149], v[102:103] op_sel_hi:[1,0]
	v_mov_b32_e32 v116, v99
	v_pk_mul_f32 v[98:99], v[98:99], v[100:101]
	v_pk_mul_f32 v[104:105], v[104:105], v[108:109]
	v_pk_mul_f32 v[106:107], v[106:107], v[102:103]
	v_mov_b32_e32 v102, v112
	v_mov_b32_e32 v103, v115
	v_pk_fma_f32 v[100:101], v[124:125], v[126:127], v[98:99] neg_lo:[0,0,1] neg_hi:[0,0,1]
	v_pk_fma_f32 v[98:99], v[116:117], v[110:111], v[118:119]
	v_pk_mul_f32 v[110:111], v[102:103], v[104:105]
	v_mov_b32_e32 v103, v112
	v_pk_mov_b32 v[116:117], v[104:105], v[106:107] op_sel:[1,0]
	v_mov_b32_e32 v112, v115
	v_pk_mov_b32 v[104:105], v[106:107], v[104:105] op_sel:[1,0]
	v_mov_b32_e32 v108, v113
	v_mov_b32_e32 v109, v114
	v_mov_b32_e32 v102, v114
	v_pk_mul_f32 v[104:105], v[112:113], v[104:105]
	s_nop 0
	v_pk_fma_f32 v[102:103], v[102:103], v[116:117], v[104:105] neg_lo:[0,0,1] neg_hi:[0,0,1]
	v_pk_fma_f32 v[104:105], v[108:109], v[106:107], v[110:111]
	s_and_b64 vcc, exec, s[42:43]
	s_cbranch_vccz .LBB0_792
	s_branch .LBB0_793

.LBB0_797:
	v_mov_b32_e32 v105, v175
	s_nop 0
	v_mov_b32_e32 v91, v87
	v_lshl_add_u32 v90, v105, 2, s97
	ds_read_b32 v104, v90 offset:192
	v_mov_b32_e32 v87, v83
	v_mov_b32_e32 v90, v82
	v_add3_u32 v107, v105, s94, 48
	v_add_u32_e32 v106, s66, v107
	s_waitcnt lgkmcnt(0)
	v_pk_mul_f32 v[102:103], v[86:87], v[104:105] op_sel_hi:[1,0]
	v_mov_b32_e32 v86, v84
	v_mov_b32_e32 v87, v89
	v_pk_mul_f32 v[96:97], v[86:87], v[104:105] op_sel_hi:[1,0]
	v_mov_b32_e32 v87, v79
	v_mov_b32_e32 v79, v75
	v_mov_b32_e32 v89, v85
	v_pk_mul_f32 v[94:95], v[78:79], v[104:105] op_sel_hi:[1,0]
	v_mov_b32_e32 v78, v76
	v_mov_b32_e32 v79, v81
	v_mov_b32_e32 v81, v77
	v_pk_mul_f32 v[100:101], v[90:91], v[104:105] op_sel_hi:[1,0]
	v_pk_mul_f32 v[98:99], v[88:89], v[104:105] op_sel_hi:[1,0]
	v_mov_b32_e32 v86, v74
	v_pk_mul_f32 v[88:89], v[78:79], v[104:105] op_sel_hi:[1,0]
	v_pk_mul_f32 v[90:91], v[80:81], v[104:105] op_sel_hi:[1,0]
	v_pk_mul_f32 v[92:93], v[86:87], v[104:105] op_sel_hi:[1,0]
	s_and_b64 vcc, exec, s[40:41]
	v_pk_mov_b32 v[86:87], v[88:89], v[90:91] op_sel:[1,0]
	s_cbranch_vccnz .LBB0_799
	v_mul_f32_e32 v74, v102, v102
	v_mul_f32_e32 v75, v103, v103
	v_mul_f32_e32 v76, v100, v100
	v_mul_f32_e32 v77, v101, v101
	v_mul_f32_e32 v78, v98, v98
	v_mul_f32_e32 v79, v99, v99
	v_add_f32_e32 v74, v74, v77
	v_mul_f32_e32 v80, v96, v96
	v_mul_f32_e32 v81, v97, v97
	v_add_f32_e32 v74, v78, v74
	v_add_f32_e32 v74, v81, v74
	v_add_f32_e32 v74, v76, v74
	v_add_f32_e32 v74, v75, v74
	v_add_f32_e32 v74, v80, v74
	v_add_f32_e32 v74, v79, v74
	v_fmac_f32_e32 v74, v94, v94
	v_mul_f32_e32 v82, v86, v86
	v_mul_f32_e32 v83, v87, v87
	v_fmac_f32_e32 v74, v93, v93
	v_pk_mov_b32 v[84:85], v[94:95], v[92:93] op_sel:[1,0]
	v_add_f32_e32 v74, v83, v74
	v_mul_f32_e32 v84, v84, v84
	v_mul_f32_e32 v85, v85, v85
	v_add_f32_e32 v74, v82, v74
	v_and_b32_e32 v76, 64, v238
	v_pk_mov_b32 v[86:87], v[90:91], v[88:89] op_sel:[1,0]
	v_add_f32_e32 v74, v85, v74
	v_xor_b32_e32 v75, 16, v238
	v_add_u32_e32 v76, 64, v76
	v_mul_f32_e32 v86, v86, v86
	v_mul_f32_e32 v87, v87, v87
	v_add_f32_e32 v74, v84, v74
	v_cmp_lt_i32_e32 vcc, v75, v76
	v_add_f32_e32 v74, v87, v74
	v_add_f32_e32 v74, v86, v74
	v_cndmask_b32_e32 v75, v238, v75, vcc
	v_lshlrev_b32_e32 v75, 2, v75
	v_mov_b32_e32 v75, v74
	s_nop 1
	v_permlane16_swap_b32 v75, v74
	v_readlane_b32 s5, v253, 18
	s_waitcnt lgkmcnt(0)
	v_add_f32_e32 v74, v74, v75
	v_xor_b32_e32 v75, 32, v238
	v_cmp_lt_i32_e32 vcc, v75, v76
	s_nop 1
	v_cndmask_b32_e32 v75, v238, v75, vcc
	v_lshlrev_b32_e32 v75, 2, v75
	v_mov_b32_e32 v75, v74
	s_nop 1
	v_permlane32_swap_b32 v75, v74
	s_waitcnt lgkmcnt(0)
	v_add_f32_e32 v74, v74, v75
	v_fmamk_f32 v74, v74, 0x3c800000, v236
	v_rsq_f32_e32 v86, v74
	v_lshrrev_b32_e32 v74, 2, v106
	v_and_b32_e32 v74, 0x3f0, v74
	v_add_u32_e32 v74, v74, v177
	v_lshl_add_u32 v78, v74, 3, s5
	ds_read_b128 v[74:77], v78
	ds_read_b128 v[80:83], v78 offset:16
	v_pk_mul_f32 v[78:79], v[54:55], v[86:87] op_sel_hi:[1,0]
	v_pk_mul_f32 v[84:85], v[154:155], v[86:87] op_sel_hi:[1,0]
	v_pk_mul_f32 v[78:79], v[100:101], v[78:79]
	v_pk_mul_f32 v[84:85], v[102:103], v[84:85]
	s_waitcnt lgkmcnt(0)
	v_mov_b32_e32 v101, v76
	v_mov_b32_e32 v102, v74
	v_mov_b32_e32 v103, v77
	v_mov_b32_e32 v108, v76
	v_mov_b32_e32 v109, v74
	v_mov_b32_e32 v74, v77
	v_pk_mov_b32 v[76:77], v[84:85], v[78:79] op_sel:[1,0]
	v_mov_b32_e32 v100, v75
	v_pk_mul_f32 v[102:103], v[102:103], v[78:79]
	v_pk_mul_f32 v[74:75], v[74:75], v[76:77]
	v_pk_mul_f32 v[76:77], v[56:57], v[86:87] op_sel_hi:[1,0]
	v_pk_mov_b32 v[110:111], v[78:79], v[84:85] op_sel:[1,0]
	v_pk_fma_f32 v[78:79], v[100:101], v[84:85], v[102:103]
	v_pk_mul_f32 v[76:77], v[96:97], v[76:77]
	v_mov_b32_e32 v97, v82
	v_mov_b32_e32 v100, v82
	v_lshlrev_b32_e32 v82, 4, v107
	v_pk_mul_f32 v[84:85], v[152:153], v[86:87] op_sel_hi:[1,0]
	v_and_b32_e32 v82, 0x3f0, v82
	v_pk_mul_f32 v[84:85], v[98:99], v[84:85]
	v_mov_b32_e32 v98, v80
	v_mov_b32_e32 v99, v83
	v_add_u32_e32 v82, v82, v177
	v_mov_b32_e32 v96, v81
	v_pk_mul_f32 v[98:99], v[98:99], v[76:77]
	v_mov_b32_e32 v101, v80
	v_pk_mov_b32 v[102:103], v[76:77], v[84:85] op_sel:[1,0]
	v_mov_b32_e32 v80, v83
	v_pk_mov_b32 v[76:77], v[84:85], v[76:77] op_sel:[1,0]
	v_lshl_add_u32 v87, v82, 3, s5
	v_pk_mul_f32 v[76:77], v[80:81], v[76:77]
	v_pk_fma_f32 v[80:81], v[96:97], v[84:85], v[98:99]
	ds_read_b128 v[82:85], v87
	ds_read_b128 v[96:99], v87 offset:16
	v_pk_fma_f32 v[76:77], v[100:101], v[102:103], v[76:77] neg_lo:[0,0,1] neg_hi:[0,0,1]
	v_pk_mul_f32 v[100:101], v[46:47], v[86:87] op_sel_hi:[1,0]
	v_pk_fma_f32 v[74:75], v[108:109], v[110:111], v[74:75] neg_lo:[0,0,1] neg_hi:[0,0,1]
	v_pk_mul_f32 v[92:93], v[92:93], v[100:101]
	v_pk_mul_f32 v[100:101], v[150:151], v[86:87] op_sel_hi:[1,0]
	s_waitcnt lgkmcnt(0)
	v_mov_b32_e32 v102, v82
	v_pk_mul_f32 v[94:95], v[94:95], v[100:101]
	v_mov_b32_e32 v103, v85
	v_mov_b32_e32 v101, v84
	v_pk_mul_f32 v[102:103], v[102:103], v[92:93]
	v_mov_b32_e32 v108, v84
	v_mov_b32_e32 v109, v82
	v_pk_mov_b32 v[110:111], v[92:93], v[94:95] op_sel:[1,0]
	v_mov_b32_e32 v82, v85
	v_pk_mov_b32 v[84:85], v[94:95], v[92:93] op_sel:[1,0]
	v_pk_mul_f32 v[92:93], v[48:49], v[86:87] op_sel_hi:[1,0]
	v_pk_mul_f32 v[86:87], v[148:149], v[86:87] op_sel_hi:[1,0]
	v_mov_b32_e32 v100, v83
	v_pk_mul_f32 v[82:83], v[82:83], v[84:85]
	v_pk_mul_f32 v[88:89], v[88:89], v[92:93]
	v_pk_mul_f32 v[90:91], v[90:91], v[86:87]
	v_mov_b32_e32 v86, v96
	v_mov_b32_e32 v87, v99
	v_pk_fma_f32 v[84:85], v[108:109], v[110:111], v[82:83] neg_lo:[0,0,1] neg_hi:[0,0,1]
	v_pk_fma_f32 v[82:83], v[100:101], v[94:95], v[102:103]
	v_pk_mul_f32 v[94:95], v[86:87], v[88:89]
	v_mov_b32_e32 v87, v96
	v_pk_mov_b32 v[100:101], v[88:89], v[90:91] op_sel:[1,0]
	v_mov_b32_e32 v96, v99
	v_pk_mov_b32 v[88:89], v[90:91], v[88:89] op_sel:[1,0]
	v_mov_b32_e32 v92, v97
	v_mov_b32_e32 v93, v98
	v_mov_b32_e32 v86, v98
	v_pk_mul_f32 v[88:89], v[96:97], v[88:89]
	s_nop 0
	v_pk_fma_f32 v[86:87], v[86:87], v[100:101], v[88:89] neg_lo:[0,0,1] neg_hi:[0,0,1]
	v_pk_fma_f32 v[88:89], v[92:93], v[90:91], v[94:95]
	s_and_b64 vcc, exec, s[42:43]
	s_cbranch_vccz .LBB0_800
	s_branch .LBB0_801

.LBB0_805:
	v_mov_b32_e32 v89, v175
	s_nop 0
	v_mov_b32_e32 v75, v71
	v_lshl_add_u32 v74, v89, 2, s97
	ds_read_b32 v88, v74 offset:512
	v_mov_b32_e32 v71, v67
	v_mov_b32_e32 v74, v66
	s_addk_i32 s4, 0x80
	v_add_u32_e32 v90, s4, v89
	s_waitcnt lgkmcnt(0)
	v_pk_mul_f32 v[86:87], v[70:71], v[88:89] op_sel_hi:[1,0]
	v_mov_b32_e32 v70, v68
	v_mov_b32_e32 v71, v73
	v_pk_mul_f32 v[80:81], v[70:71], v[88:89] op_sel_hi:[1,0]
	v_mov_b32_e32 v71, v63
	v_mov_b32_e32 v63, v59
	v_mov_b32_e32 v73, v69
	v_pk_mul_f32 v[78:79], v[62:63], v[88:89] op_sel_hi:[1,0]
	v_mov_b32_e32 v62, v60
	v_mov_b32_e32 v63, v65
	v_mov_b32_e32 v65, v61
	v_pk_mul_f32 v[84:85], v[74:75], v[88:89] op_sel_hi:[1,0]
	v_pk_mul_f32 v[82:83], v[72:73], v[88:89] op_sel_hi:[1,0]
	v_mov_b32_e32 v70, v58
	v_pk_mul_f32 v[72:73], v[62:63], v[88:89] op_sel_hi:[1,0]
	v_pk_mul_f32 v[74:75], v[64:65], v[88:89] op_sel_hi:[1,0]
	v_pk_mul_f32 v[76:77], v[70:71], v[88:89] op_sel_hi:[1,0]
	s_and_b64 vcc, exec, s[40:41]
	v_pk_mov_b32 v[70:71], v[72:73], v[74:75] op_sel:[1,0]
	s_cbranch_vccnz .LBB0_807
	v_mul_f32_e32 v58, v86, v86
	v_mul_f32_e32 v59, v87, v87
	v_mul_f32_e32 v60, v84, v84
	v_mul_f32_e32 v61, v85, v85
	v_mul_f32_e32 v62, v82, v82
	v_mul_f32_e32 v63, v83, v83
	v_add_f32_e32 v58, v58, v61
	v_mul_f32_e32 v64, v80, v80
	v_mul_f32_e32 v65, v81, v81
	v_add_f32_e32 v58, v62, v58
	v_add_f32_e32 v58, v65, v58
	v_add_f32_e32 v58, v60, v58
	v_add_f32_e32 v58, v59, v58
	v_add_f32_e32 v58, v64, v58
	v_add_f32_e32 v58, v63, v58
	v_fmac_f32_e32 v58, v78, v78
	v_mul_f32_e32 v66, v70, v70
	v_mul_f32_e32 v67, v71, v71
	v_fmac_f32_e32 v58, v77, v77
	v_pk_mov_b32 v[68:69], v[78:79], v[76:77] op_sel:[1,0]
	v_add_f32_e32 v58, v67, v58
	v_mul_f32_e32 v68, v68, v68
	v_mul_f32_e32 v69, v69, v69
	v_add_f32_e32 v58, v66, v58
	v_and_b32_e32 v60, 64, v238
	v_pk_mov_b32 v[70:71], v[74:75], v[72:73] op_sel:[1,0]
	v_add_f32_e32 v58, v69, v58
	v_xor_b32_e32 v59, 16, v238
	v_add_u32_e32 v60, 64, v60
	v_mul_f32_e32 v70, v70, v70
	v_mul_f32_e32 v71, v71, v71
	v_add_f32_e32 v58, v68, v58
	v_cmp_lt_i32_e32 vcc, v59, v60
	v_add_f32_e32 v58, v71, v58
	v_add_f32_e32 v58, v70, v58
	v_cndmask_b32_e32 v59, v238, v59, vcc
	v_lshlrev_b32_e32 v59, 2, v59
	v_mov_b32_e32 v59, v58
	s_nop 1
	v_permlane16_swap_b32 v59, v58
	v_readlane_b32 s4, v253, 18
	s_waitcnt lgkmcnt(0)
	v_add_f32_e32 v58, v58, v59
	v_xor_b32_e32 v59, 32, v238
	v_cmp_lt_i32_e32 vcc, v59, v60
	s_nop 1
	v_cndmask_b32_e32 v59, v238, v59, vcc
	v_lshlrev_b32_e32 v59, 2, v59
	v_mov_b32_e32 v59, v58
	s_nop 1
	v_permlane32_swap_b32 v59, v58
	s_waitcnt lgkmcnt(0)
	v_add_f32_e32 v58, v58, v59
	v_fmamk_f32 v58, v58, 0x3c800000, v236
	v_rsq_f32_e32 v70, v58
	v_lshrrev_b32_e32 v58, 2, v90
	v_and_b32_e32 v58, 0x3f0, v58
	v_add_u32_e32 v58, v58, v177
	v_lshl_add_u32 v62, v58, 3, s4
	ds_read_b128 v[58:61], v62
	ds_read_b128 v[64:67], v62 offset:16
	v_pk_mul_f32 v[62:63], v[54:55], v[70:71] op_sel_hi:[1,0]
	v_pk_mul_f32 v[68:69], v[154:155], v[70:71] op_sel_hi:[1,0]
	v_pk_mul_f32 v[62:63], v[84:85], v[62:63]
	v_pk_mul_f32 v[68:69], v[86:87], v[68:69]
	s_waitcnt lgkmcnt(0)
	v_mov_b32_e32 v85, v60
	v_mov_b32_e32 v86, v58
	v_mov_b32_e32 v87, v61
	v_mov_b32_e32 v92, v60
	v_mov_b32_e32 v93, v58
	v_mov_b32_e32 v58, v61
	v_pk_mov_b32 v[60:61], v[68:69], v[62:63] op_sel:[1,0]
	v_mov_b32_e32 v84, v59
	v_pk_mul_f32 v[86:87], v[86:87], v[62:63]
	v_pk_mul_f32 v[58:59], v[58:59], v[60:61]
	v_pk_mul_f32 v[60:61], v[56:57], v[70:71] op_sel_hi:[1,0]
	v_pk_mov_b32 v[94:95], v[62:63], v[68:69] op_sel:[1,0]
	v_pk_fma_f32 v[62:63], v[84:85], v[68:69], v[86:87]
	v_pk_mul_f32 v[60:61], v[80:81], v[60:61]
	v_mov_b32_e32 v81, v66
	v_mov_b32_e32 v84, v66
	v_lshlrev_b32_e32 v66, 4, v89
	v_pk_mul_f32 v[68:69], v[152:153], v[70:71] op_sel_hi:[1,0]
	v_and_b32_e32 v66, 0x3f0, v66
	v_pk_mul_f32 v[68:69], v[82:83], v[68:69]
	v_mov_b32_e32 v82, v64
	v_mov_b32_e32 v83, v67
	v_add_u32_e32 v66, v66, v177
	v_mov_b32_e32 v80, v65
	v_pk_mul_f32 v[82:83], v[82:83], v[60:61]
	v_mov_b32_e32 v85, v64
	v_pk_mov_b32 v[86:87], v[60:61], v[68:69] op_sel:[1,0]
	v_mov_b32_e32 v64, v67
	v_pk_mov_b32 v[60:61], v[68:69], v[60:61] op_sel:[1,0]
	v_lshl_add_u32 v71, v66, 3, s4
	v_pk_mul_f32 v[60:61], v[64:65], v[60:61]
	v_pk_fma_f32 v[64:65], v[80:81], v[68:69], v[82:83]
	ds_read_b128 v[66:69], v71
	ds_read_b128 v[80:83], v71 offset:16
	v_pk_fma_f32 v[60:61], v[84:85], v[86:87], v[60:61] neg_lo:[0,0,1] neg_hi:[0,0,1]
	v_pk_mul_f32 v[84:85], v[46:47], v[70:71] op_sel_hi:[1,0]
	v_pk_fma_f32 v[58:59], v[92:93], v[94:95], v[58:59] neg_lo:[0,0,1] neg_hi:[0,0,1]
	v_pk_mul_f32 v[76:77], v[76:77], v[84:85]
	v_pk_mul_f32 v[84:85], v[150:151], v[70:71] op_sel_hi:[1,0]
	s_waitcnt lgkmcnt(0)
	v_mov_b32_e32 v86, v66
	v_pk_mul_f32 v[78:79], v[78:79], v[84:85]
	v_mov_b32_e32 v87, v69
	v_mov_b32_e32 v85, v68
	v_pk_mul_f32 v[86:87], v[86:87], v[76:77]
	v_mov_b32_e32 v92, v68
	v_mov_b32_e32 v93, v66
	v_pk_mov_b32 v[94:95], v[76:77], v[78:79] op_sel:[1,0]
	v_mov_b32_e32 v66, v69
	v_pk_mov_b32 v[68:69], v[78:79], v[76:77] op_sel:[1,0]
	v_pk_mul_f32 v[76:77], v[48:49], v[70:71] op_sel_hi:[1,0]
	v_pk_mul_f32 v[70:71], v[148:149], v[70:71] op_sel_hi:[1,0]
	v_mov_b32_e32 v84, v67
	v_pk_mul_f32 v[66:67], v[66:67], v[68:69]
	v_pk_mul_f32 v[72:73], v[72:73], v[76:77]
	v_pk_mul_f32 v[74:75], v[74:75], v[70:71]
	v_mov_b32_e32 v70, v80
	v_mov_b32_e32 v71, v83
	v_pk_fma_f32 v[68:69], v[92:93], v[94:95], v[66:67] neg_lo:[0,0,1] neg_hi:[0,0,1]
	v_pk_fma_f32 v[66:67], v[84:85], v[78:79], v[86:87]
	v_pk_mul_f32 v[78:79], v[70:71], v[72:73]
	v_mov_b32_e32 v71, v80
	v_pk_mov_b32 v[84:85], v[72:73], v[74:75] op_sel:[1,0]
	v_mov_b32_e32 v80, v83
	v_pk_mov_b32 v[72:73], v[74:75], v[72:73] op_sel:[1,0]
	v_mov_b32_e32 v76, v81
	v_mov_b32_e32 v77, v82
	v_mov_b32_e32 v70, v82
	v_pk_mul_f32 v[72:73], v[80:81], v[72:73]
	s_nop 0
	v_pk_fma_f32 v[70:71], v[70:71], v[84:85], v[72:73] neg_lo:[0,0,1] neg_hi:[0,0,1]
	v_pk_fma_f32 v[72:73], v[76:77], v[74:75], v[78:79]
	s_and_b64 vcc, exec, s[42:43]
	s_cbranch_vccz .LBB0_808
	s_branch .LBB0_809

.LBB0_813:
	v_mov_b32_e32 v73, v175
	s_nop 0
	v_mov_b32_e32 v59, v51
	v_lshl_add_u32 v58, v73, 2, s97
	ds_read_b32 v72, v58 offset:576
	v_mov_b32_e32 v51, v43
	s_add_i32 s4, s94, 0x90
	v_mov_b32_e32 v58, v42
	v_add_u32_e32 v75, s4, v73
	s_waitcnt lgkmcnt(0)
	v_pk_mul_f32 v[70:71], v[50:51], v[72:73] op_sel_hi:[1,0]
	v_mov_b32_e32 v50, v44
	v_mov_b32_e32 v51, v53
	v_pk_mul_f32 v[64:65], v[50:51], v[72:73] op_sel_hi:[1,0]
	v_mov_b32_e32 v51, v39
	v_mov_b32_e32 v39, v35
	v_mov_b32_e32 v53, v45
	v_pk_mul_f32 v[62:63], v[38:39], v[72:73] op_sel_hi:[1,0]
	v_mov_b32_e32 v38, v36
	v_mov_b32_e32 v39, v41
	v_mov_b32_e32 v41, v37
	v_pk_mul_f32 v[68:69], v[58:59], v[72:73] op_sel_hi:[1,0]
	v_pk_mul_f32 v[66:67], v[52:53], v[72:73] op_sel_hi:[1,0]
	v_mov_b32_e32 v50, v34
	v_pk_mul_f32 v[52:53], v[38:39], v[72:73] op_sel_hi:[1,0]
	v_pk_mul_f32 v[58:59], v[40:41], v[72:73] op_sel_hi:[1,0]
	v_add_u32_e32 v74, s66, v75
	v_pk_mul_f32 v[60:61], v[50:51], v[72:73] op_sel_hi:[1,0]
	s_and_b64 vcc, exec, s[40:41]
	v_pk_mov_b32 v[50:51], v[52:53], v[58:59] op_sel:[1,0]
	s_cbranch_vccnz .LBB0_815
	v_mul_f32_e32 v34, v70, v70
	v_mul_f32_e32 v35, v71, v71
	v_mul_f32_e32 v36, v68, v68
	v_mul_f32_e32 v37, v69, v69
	v_mul_f32_e32 v38, v66, v66
	v_mul_f32_e32 v39, v67, v67
	v_add_f32_e32 v34, v34, v37
	v_mul_f32_e32 v40, v64, v64
	v_mul_f32_e32 v41, v65, v65
	v_add_f32_e32 v34, v38, v34
	v_add_f32_e32 v34, v41, v34
	v_add_f32_e32 v34, v36, v34
	v_add_f32_e32 v34, v35, v34
	v_add_f32_e32 v34, v40, v34
	v_add_f32_e32 v34, v39, v34
	v_fmac_f32_e32 v34, v62, v62
	v_mul_f32_e32 v42, v50, v50
	v_mul_f32_e32 v43, v51, v51
	v_fmac_f32_e32 v34, v61, v61
	v_pk_mov_b32 v[44:45], v[62:63], v[60:61] op_sel:[1,0]
	v_add_f32_e32 v34, v43, v34
	v_mul_f32_e32 v44, v44, v44
	v_mul_f32_e32 v45, v45, v45
	v_add_f32_e32 v34, v42, v34
	v_and_b32_e32 v36, 64, v238
	v_pk_mov_b32 v[50:51], v[58:59], v[52:53] op_sel:[1,0]
	v_add_f32_e32 v34, v45, v34
	v_xor_b32_e32 v35, 16, v238
	v_add_u32_e32 v36, 64, v36
	v_mul_f32_e32 v50, v50, v50
	v_mul_f32_e32 v51, v51, v51
	v_add_f32_e32 v34, v44, v34
	v_cmp_lt_i32_e32 vcc, v35, v36
	v_add_f32_e32 v34, v51, v34
	v_add_f32_e32 v34, v50, v34
	v_cndmask_b32_e32 v35, v238, v35, vcc
	v_lshlrev_b32_e32 v35, 2, v35
	v_mov_b32_e32 v35, v34
	s_nop 1
	v_permlane16_swap_b32 v35, v34
	v_readlane_b32 s4, v253, 18
	s_waitcnt lgkmcnt(0)
	v_add_f32_e32 v34, v34, v35
	v_xor_b32_e32 v35, 32, v238
	v_cmp_lt_i32_e32 vcc, v35, v36
	s_nop 1
	v_cndmask_b32_e32 v35, v238, v35, vcc
	v_lshlrev_b32_e32 v35, 2, v35
	v_mov_b32_e32 v35, v34
	s_nop 1
	v_permlane32_swap_b32 v35, v34
	s_waitcnt lgkmcnt(0)
	v_add_f32_e32 v34, v34, v35
	v_fmamk_f32 v34, v34, 0x3c800000, v236
	v_rsq_f32_e32 v50, v34
	v_lshrrev_b32_e32 v34, 2, v74
	v_and_b32_e32 v34, 0x3f0, v34
	v_add_u32_e32 v34, v34, v177
	v_lshl_add_u32 v38, v34, 3, s4
	ds_read_b128 v[34:37], v38
	ds_read_b128 v[40:43], v38 offset:16
	v_pk_mul_f32 v[38:39], v[54:55], v[50:51] op_sel_hi:[1,0]
	v_pk_mul_f32 v[44:45], v[154:155], v[50:51] op_sel_hi:[1,0]
	v_pk_mul_f32 v[38:39], v[68:69], v[38:39]
	v_pk_mul_f32 v[44:45], v[70:71], v[44:45]
	s_waitcnt lgkmcnt(0)
	v_mov_b32_e32 v69, v36
	v_mov_b32_e32 v70, v34
	v_mov_b32_e32 v71, v37
	v_mov_b32_e32 v76, v36
	v_mov_b32_e32 v77, v34
	v_mov_b32_e32 v34, v37
	v_pk_mov_b32 v[36:37], v[44:45], v[38:39] op_sel:[1,0]
	v_mov_b32_e32 v68, v35
	v_pk_mul_f32 v[70:71], v[70:71], v[38:39]
	v_pk_mul_f32 v[34:35], v[34:35], v[36:37]
	v_pk_mul_f32 v[36:37], v[56:57], v[50:51] op_sel_hi:[1,0]
	v_pk_mov_b32 v[78:79], v[38:39], v[44:45] op_sel:[1,0]
	v_pk_fma_f32 v[38:39], v[68:69], v[44:45], v[70:71]
	v_pk_mul_f32 v[36:37], v[64:65], v[36:37]
	v_mov_b32_e32 v65, v42
	v_mov_b32_e32 v68, v42
	v_lshlrev_b32_e32 v42, 4, v75
	v_pk_mul_f32 v[44:45], v[152:153], v[50:51] op_sel_hi:[1,0]
	v_and_b32_e32 v42, 0x3f0, v42
	v_pk_mul_f32 v[44:45], v[66:67], v[44:45]
	v_mov_b32_e32 v66, v40
	v_mov_b32_e32 v67, v43
	v_add_u32_e32 v42, v42, v177
	v_mov_b32_e32 v64, v41
	v_pk_mul_f32 v[66:67], v[66:67], v[36:37]
	v_mov_b32_e32 v69, v40
	v_pk_mov_b32 v[70:71], v[36:37], v[44:45] op_sel:[1,0]
	v_mov_b32_e32 v40, v43
	v_pk_mov_b32 v[36:37], v[44:45], v[36:37] op_sel:[1,0]
	v_lshl_add_u32 v51, v42, 3, s4
	v_pk_mul_f32 v[36:37], v[40:41], v[36:37]
	v_pk_fma_f32 v[40:41], v[64:65], v[44:45], v[66:67]
	ds_read_b128 v[42:45], v51
	ds_read_b128 v[64:67], v51 offset:16
	v_pk_fma_f32 v[36:37], v[68:69], v[70:71], v[36:37] neg_lo:[0,0,1] neg_hi:[0,0,1]
	v_pk_mul_f32 v[68:69], v[46:47], v[50:51] op_sel_hi:[1,0]
	v_pk_fma_f32 v[34:35], v[76:77], v[78:79], v[34:35] neg_lo:[0,0,1] neg_hi:[0,0,1]
	v_pk_mul_f32 v[60:61], v[60:61], v[68:69]
	v_pk_mul_f32 v[68:69], v[150:151], v[50:51] op_sel_hi:[1,0]
	s_waitcnt lgkmcnt(0)
	v_mov_b32_e32 v70, v42
	v_pk_mul_f32 v[62:63], v[62:63], v[68:69]
	v_mov_b32_e32 v71, v45
	v_mov_b32_e32 v69, v44
	v_pk_mul_f32 v[70:71], v[70:71], v[60:61]
	v_mov_b32_e32 v76, v44
	v_mov_b32_e32 v77, v42
	v_pk_mov_b32 v[78:79], v[60:61], v[62:63] op_sel:[1,0]
	v_mov_b32_e32 v42, v45
	v_pk_mov_b32 v[44:45], v[62:63], v[60:61] op_sel:[1,0]
	v_pk_mul_f32 v[60:61], v[48:49], v[50:51] op_sel_hi:[1,0]
	v_pk_mul_f32 v[50:51], v[148:149], v[50:51] op_sel_hi:[1,0]
	v_mov_b32_e32 v68, v43
	v_pk_mul_f32 v[42:43], v[42:43], v[44:45]
	v_pk_mul_f32 v[52:53], v[52:53], v[60:61]
	v_pk_mul_f32 v[58:59], v[58:59], v[50:51]
	v_mov_b32_e32 v50, v64
	v_mov_b32_e32 v51, v67
	v_pk_fma_f32 v[44:45], v[76:77], v[78:79], v[42:43] neg_lo:[0,0,1] neg_hi:[0,0,1]
	v_pk_fma_f32 v[42:43], v[68:69], v[62:63], v[70:71]
	v_pk_mul_f32 v[62:63], v[50:51], v[52:53]
	v_mov_b32_e32 v51, v64
	v_pk_mov_b32 v[68:69], v[52:53], v[58:59] op_sel:[1,0]
	v_mov_b32_e32 v64, v67
	v_pk_mov_b32 v[52:53], v[58:59], v[52:53] op_sel:[1,0]
	v_mov_b32_e32 v60, v65
	v_mov_b32_e32 v61, v66
	v_mov_b32_e32 v50, v66
	v_pk_mul_f32 v[52:53], v[64:65], v[52:53]
	s_nop 0
	v_pk_fma_f32 v[50:51], v[50:51], v[68:69], v[52:53] neg_lo:[0,0,1] neg_hi:[0,0,1]
	v_pk_fma_f32 v[52:53], v[60:61], v[58:59], v[62:63]
	s_and_b64 vcc, exec, s[42:43]
	s_cbranch_vccz .LBB0_816
	s_branch .LBB0_817

.LBB0_821:
	v_mov_b32_e32 v53, v175
	s_nop 0
	v_mov_b32_e32 v35, v29
	v_lshl_add_u32 v34, v53, 2, s97
	ds_read_b32 v52, v34 offset:640
	v_mov_b32_e32 v29, v25
	s_add_i32 s4, s94, 0xa0
	v_mov_b32_e32 v34, v24
	v_add_u32_e32 v59, s4, v53
	s_waitcnt lgkmcnt(0)
	v_pk_mul_f32 v[50:51], v[28:29], v[52:53] op_sel_hi:[1,0]
	v_mov_b32_e32 v28, v26
	v_mov_b32_e32 v29, v31
	v_pk_mul_f32 v[40:41], v[28:29], v[52:53] op_sel_hi:[1,0]
	v_mov_b32_e32 v29, v21
	v_mov_b32_e32 v21, v17
	v_mov_b32_e32 v31, v27
	v_pk_mul_f32 v[38:39], v[20:21], v[52:53] op_sel_hi:[1,0]
	v_mov_b32_e32 v20, v18
	v_mov_b32_e32 v21, v23
	v_mov_b32_e32 v23, v19
	v_pk_mul_f32 v[44:45], v[34:35], v[52:53] op_sel_hi:[1,0]
	v_pk_mul_f32 v[42:43], v[30:31], v[52:53] op_sel_hi:[1,0]
	v_mov_b32_e32 v28, v16
	v_pk_mul_f32 v[30:31], v[20:21], v[52:53] op_sel_hi:[1,0]
	v_pk_mul_f32 v[34:35], v[22:23], v[52:53] op_sel_hi:[1,0]
	v_add_u32_e32 v58, s66, v59
	v_pk_mul_f32 v[36:37], v[28:29], v[52:53] op_sel_hi:[1,0]
	s_and_b64 vcc, exec, s[40:41]
	v_pk_mov_b32 v[28:29], v[30:31], v[34:35] op_sel:[1,0]
	s_cbranch_vccnz .LBB0_823
	v_mul_f32_e32 v16, v50, v50
	v_mul_f32_e32 v17, v51, v51
	v_mul_f32_e32 v18, v44, v44
	v_mul_f32_e32 v19, v45, v45
	v_mul_f32_e32 v20, v42, v42
	v_mul_f32_e32 v21, v43, v43
	v_add_f32_e32 v16, v16, v19
	v_mul_f32_e32 v22, v40, v40
	v_mul_f32_e32 v23, v41, v41
	v_add_f32_e32 v16, v20, v16
	v_add_f32_e32 v16, v23, v16
	v_add_f32_e32 v16, v18, v16
	v_add_f32_e32 v16, v17, v16
	v_add_f32_e32 v16, v22, v16
	v_add_f32_e32 v16, v21, v16
	v_fmac_f32_e32 v16, v38, v38
	v_mul_f32_e32 v24, v28, v28
	v_mul_f32_e32 v25, v29, v29
	v_fmac_f32_e32 v16, v37, v37
	v_pk_mov_b32 v[26:27], v[38:39], v[36:37] op_sel:[1,0]
	v_add_f32_e32 v16, v25, v16
	v_mul_f32_e32 v26, v26, v26
	v_mul_f32_e32 v27, v27, v27
	v_add_f32_e32 v16, v24, v16
	v_and_b32_e32 v18, 64, v238
	v_pk_mov_b32 v[28:29], v[34:35], v[30:31] op_sel:[1,0]
	v_add_f32_e32 v16, v27, v16
	v_xor_b32_e32 v17, 16, v238
	v_add_u32_e32 v18, 64, v18
	v_mul_f32_e32 v28, v28, v28
	v_mul_f32_e32 v29, v29, v29
	v_add_f32_e32 v16, v26, v16
	v_cmp_lt_i32_e32 vcc, v17, v18
	v_add_f32_e32 v16, v29, v16
	v_add_f32_e32 v16, v28, v16
	v_cndmask_b32_e32 v17, v238, v17, vcc
	v_lshlrev_b32_e32 v17, 2, v17
	v_mov_b32_e32 v17, v16
	s_nop 1
	v_permlane16_swap_b32 v17, v16
	v_readlane_b32 s4, v253, 18
	s_waitcnt lgkmcnt(0)
	v_add_f32_e32 v16, v16, v17
	v_xor_b32_e32 v17, 32, v238
	v_cmp_lt_i32_e32 vcc, v17, v18
	s_nop 1
	v_cndmask_b32_e32 v17, v238, v17, vcc
	v_lshlrev_b32_e32 v17, 2, v17
	v_mov_b32_e32 v17, v16
	s_nop 1
	v_permlane32_swap_b32 v17, v16
	s_waitcnt lgkmcnt(0)
	v_add_f32_e32 v16, v16, v17
	v_fmamk_f32 v16, v16, 0x3c800000, v236
	v_rsq_f32_e32 v28, v16
	v_lshrrev_b32_e32 v16, 2, v58
	v_and_b32_e32 v16, 0x3f0, v16
	v_add_u32_e32 v16, v16, v177
	v_lshl_add_u32 v20, v16, 3, s4
	ds_read_b128 v[16:19], v20
	ds_read_b128 v[22:25], v20 offset:16
	v_pk_mul_f32 v[20:21], v[54:55], v[28:29] op_sel_hi:[1,0]
	v_pk_mul_f32 v[26:27], v[154:155], v[28:29] op_sel_hi:[1,0]
	v_pk_mul_f32 v[20:21], v[44:45], v[20:21]
	v_pk_mul_f32 v[26:27], v[50:51], v[26:27]
	s_waitcnt lgkmcnt(0)
	v_mov_b32_e32 v45, v18
	v_mov_b32_e32 v50, v16
	v_mov_b32_e32 v51, v19
	v_mov_b32_e32 v60, v18
	v_mov_b32_e32 v61, v16
	v_mov_b32_e32 v16, v19
	v_pk_mov_b32 v[18:19], v[26:27], v[20:21] op_sel:[1,0]
	v_mov_b32_e32 v44, v17
	v_pk_mul_f32 v[50:51], v[50:51], v[20:21]
	v_pk_mul_f32 v[16:17], v[16:17], v[18:19]
	v_pk_mul_f32 v[18:19], v[56:57], v[28:29] op_sel_hi:[1,0]
	v_pk_mov_b32 v[62:63], v[20:21], v[26:27] op_sel:[1,0]
	v_pk_fma_f32 v[20:21], v[44:45], v[26:27], v[50:51]
	v_pk_mul_f32 v[18:19], v[40:41], v[18:19]
	v_mov_b32_e32 v41, v24
	v_mov_b32_e32 v44, v24
	v_lshlrev_b32_e32 v24, 4, v59
	v_pk_mul_f32 v[26:27], v[152:153], v[28:29] op_sel_hi:[1,0]
	v_and_b32_e32 v24, 0x3f0, v24
	v_pk_mul_f32 v[26:27], v[42:43], v[26:27]
	v_mov_b32_e32 v42, v22
	v_mov_b32_e32 v43, v25
	v_add_u32_e32 v24, v24, v177
	v_mov_b32_e32 v40, v23
	v_pk_mul_f32 v[42:43], v[42:43], v[18:19]
	v_mov_b32_e32 v45, v22
	v_pk_mov_b32 v[50:51], v[18:19], v[26:27] op_sel:[1,0]
	v_mov_b32_e32 v22, v25
	v_pk_mov_b32 v[18:19], v[26:27], v[18:19] op_sel:[1,0]
	v_lshl_add_u32 v29, v24, 3, s4
	v_pk_mul_f32 v[18:19], v[22:23], v[18:19]
	v_pk_fma_f32 v[22:23], v[40:41], v[26:27], v[42:43]
	ds_read_b128 v[24:27], v29
	ds_read_b128 v[40:43], v29 offset:16
	v_pk_fma_f32 v[18:19], v[44:45], v[50:51], v[18:19] neg_lo:[0,0,1] neg_hi:[0,0,1]
	v_pk_mul_f32 v[44:45], v[46:47], v[28:29] op_sel_hi:[1,0]
	v_pk_fma_f32 v[16:17], v[60:61], v[62:63], v[16:17] neg_lo:[0,0,1] neg_hi:[0,0,1]
	v_pk_mul_f32 v[36:37], v[36:37], v[44:45]
	v_pk_mul_f32 v[44:45], v[150:151], v[28:29] op_sel_hi:[1,0]
	s_waitcnt lgkmcnt(0)
	v_mov_b32_e32 v50, v24
	v_pk_mul_f32 v[38:39], v[38:39], v[44:45]
	v_mov_b32_e32 v51, v27
	v_mov_b32_e32 v45, v26
	v_pk_mul_f32 v[50:51], v[50:51], v[36:37]
	v_mov_b32_e32 v60, v26
	v_mov_b32_e32 v61, v24
	v_pk_mov_b32 v[62:63], v[36:37], v[38:39] op_sel:[1,0]
	v_mov_b32_e32 v24, v27
	v_pk_mov_b32 v[26:27], v[38:39], v[36:37] op_sel:[1,0]
	v_pk_mul_f32 v[36:37], v[48:49], v[28:29] op_sel_hi:[1,0]
	v_pk_mul_f32 v[28:29], v[148:149], v[28:29] op_sel_hi:[1,0]
	v_mov_b32_e32 v44, v25
	v_pk_mul_f32 v[24:25], v[24:25], v[26:27]
	v_pk_mul_f32 v[30:31], v[30:31], v[36:37]
	v_pk_mul_f32 v[34:35], v[34:35], v[28:29]
	v_mov_b32_e32 v28, v40
	v_mov_b32_e32 v29, v43
	v_pk_fma_f32 v[26:27], v[60:61], v[62:63], v[24:25] neg_lo:[0,0,1] neg_hi:[0,0,1]
	v_pk_fma_f32 v[24:25], v[44:45], v[38:39], v[50:51]
	v_pk_mul_f32 v[38:39], v[28:29], v[30:31]
	v_mov_b32_e32 v29, v40
	v_pk_mov_b32 v[44:45], v[30:31], v[34:35] op_sel:[1,0]
	v_mov_b32_e32 v40, v43
	v_pk_mov_b32 v[30:31], v[34:35], v[30:31] op_sel:[1,0]
	v_mov_b32_e32 v36, v41
	v_mov_b32_e32 v37, v42
	v_mov_b32_e32 v28, v42
	v_pk_mul_f32 v[30:31], v[40:41], v[30:31]
	s_nop 0
	v_pk_fma_f32 v[28:29], v[28:29], v[44:45], v[30:31] neg_lo:[0,0,1] neg_hi:[0,0,1]
	v_pk_fma_f32 v[30:31], v[36:37], v[34:35], v[38:39]
	s_and_b64 vcc, exec, s[42:43]
	s_cbranch_vccz .LBB0_824
	s_branch .LBB0_825

.LBB0_829:
	s_addk_i32 s94, 0xb0
	s_nop 0
	v_lshl_add_u32 v16, v175, 2, s97
	ds_read_b32 v30, v16 offset:704
	v_add_u32_e32 v34, s94, v175
	v_add_u32_e32 v31, s66, v34
	v_mov_b32_e32 v17, v13
	v_mov_b32_e32 v13, v9
	s_waitcnt lgkmcnt(0)
	v_pk_mul_f32 v[28:29], v[12:13], v[30:31] op_sel_hi:[1,0]
	v_mov_b32_e32 v12, v10
	v_mov_b32_e32 v13, v15
	v_pk_mul_f32 v[22:23], v[12:13], v[30:31] op_sel_hi:[1,0]
	v_mov_b32_e32 v13, v5
	v_mov_b32_e32 v5, v1
	v_mov_b32_e32 v16, v8
	v_mov_b32_e32 v15, v11
	v_pk_mul_f32 v[20:21], v[4:5], v[30:31] op_sel_hi:[1,0]
	v_mov_b32_e32 v4, v2
	v_mov_b32_e32 v5, v7
	v_mov_b32_e32 v7, v3
	v_pk_mul_f32 v[26:27], v[16:17], v[30:31] op_sel_hi:[1,0]
	v_pk_mul_f32 v[24:25], v[14:15], v[30:31] op_sel_hi:[1,0]
	v_mov_b32_e32 v12, v0
	v_pk_mul_f32 v[14:15], v[4:5], v[30:31] op_sel_hi:[1,0]
	v_pk_mul_f32 v[16:17], v[6:7], v[30:31] op_sel_hi:[1,0]
	v_pk_mul_f32 v[18:19], v[12:13], v[30:31] op_sel_hi:[1,0]
	s_and_b64 vcc, exec, s[40:41]
	v_pk_mov_b32 v[12:13], v[14:15], v[16:17] op_sel:[1,0]
	s_cbranch_vccnz .LBB0_831
	v_mul_f32_e32 v0, v28, v28
	v_mul_f32_e32 v1, v29, v29
	v_mul_f32_e32 v2, v26, v26
	v_mul_f32_e32 v3, v27, v27
	v_mul_f32_e32 v4, v24, v24
	v_mul_f32_e32 v5, v25, v25
	v_add_f32_e32 v0, v0, v3
	v_mul_f32_e32 v6, v22, v22
	v_mul_f32_e32 v7, v23, v23
	v_add_f32_e32 v0, v4, v0
	v_add_f32_e32 v0, v7, v0
	v_add_f32_e32 v0, v2, v0
	v_add_f32_e32 v0, v1, v0
	v_add_f32_e32 v0, v6, v0
	v_add_f32_e32 v0, v5, v0
	v_fmac_f32_e32 v0, v20, v20
	v_mul_f32_e32 v8, v12, v12
	v_mul_f32_e32 v9, v13, v13
	v_fmac_f32_e32 v0, v19, v19
	v_pk_mov_b32 v[10:11], v[20:21], v[18:19] op_sel:[1,0]
	v_add_f32_e32 v0, v9, v0
	v_mul_f32_e32 v10, v10, v10
	v_mul_f32_e32 v11, v11, v11
	v_add_f32_e32 v0, v8, v0
	v_and_b32_e32 v2, 64, v238
	v_pk_mov_b32 v[12:13], v[16:17], v[14:15] op_sel:[1,0]
	v_add_f32_e32 v0, v11, v0
	v_xor_b32_e32 v1, 16, v238
	v_add_u32_e32 v2, 64, v2
	v_mul_f32_e32 v12, v12, v12
	v_mul_f32_e32 v13, v13, v13
	v_add_f32_e32 v0, v10, v0
	v_cmp_lt_i32_e32 vcc, v1, v2
	v_add_f32_e32 v0, v13, v0
	v_add_f32_e32 v0, v12, v0
	v_cndmask_b32_e32 v1, v238, v1, vcc
	v_lshlrev_b32_e32 v1, 2, v1
	v_mov_b32_e32 v1, v0
	s_nop 1
	v_permlane16_swap_b32 v1, v0
	v_readlane_b32 s4, v253, 18
	s_waitcnt lgkmcnt(0)
	v_add_f32_e32 v0, v0, v1
	v_xor_b32_e32 v1, 32, v238
	v_cmp_lt_i32_e32 vcc, v1, v2
	s_nop 1
	v_cndmask_b32_e32 v1, v238, v1, vcc
	v_lshlrev_b32_e32 v1, 2, v1
	v_mov_b32_e32 v1, v0
	s_nop 1
	v_permlane32_swap_b32 v1, v0
	s_waitcnt lgkmcnt(0)
	v_add_f32_e32 v0, v0, v1
	v_fmamk_f32 v0, v0, 0x3c800000, v236
	v_rsq_f32_e32 v12, v0
	v_lshrrev_b32_e32 v0, 2, v31
	v_and_b32_e32 v0, 0x3f0, v0
	v_add_u32_e32 v0, v0, v177
	v_lshl_add_u32 v4, v0, 3, s4
	ds_read_b128 v[0:3], v4
	ds_read_b128 v[6:9], v4 offset:16
	v_pk_mul_f32 v[4:5], v[54:55], v[12:13] op_sel_hi:[1,0]
	v_pk_mul_f32 v[10:11], v[154:155], v[12:13] op_sel_hi:[1,0]
	v_pk_mul_f32 v[4:5], v[26:27], v[4:5]
	v_pk_mul_f32 v[10:11], v[28:29], v[10:11]
	s_waitcnt lgkmcnt(0)
	v_mov_b32_e32 v27, v2
	v_mov_b32_e32 v28, v0
	v_mov_b32_e32 v29, v3
	v_mov_b32_e32 v36, v2
	v_mov_b32_e32 v37, v0
	v_mov_b32_e32 v0, v3
	v_pk_mov_b32 v[2:3], v[10:11], v[4:5] op_sel:[1,0]
	v_mov_b32_e32 v26, v1
	v_pk_mul_f32 v[28:29], v[28:29], v[4:5]
	v_pk_mul_f32 v[0:1], v[0:1], v[2:3]
	v_pk_mul_f32 v[2:3], v[56:57], v[12:13] op_sel_hi:[1,0]
	v_pk_mov_b32 v[38:39], v[4:5], v[10:11] op_sel:[1,0]
	v_pk_fma_f32 v[4:5], v[26:27], v[10:11], v[28:29]
	v_pk_mul_f32 v[2:3], v[22:23], v[2:3]
	v_mov_b32_e32 v23, v8
	v_mov_b32_e32 v26, v8
	v_lshlrev_b32_e32 v8, 4, v34
	v_pk_mul_f32 v[10:11], v[152:153], v[12:13] op_sel_hi:[1,0]
	v_and_b32_e32 v8, 0x3f0, v8
	v_pk_mul_f32 v[10:11], v[24:25], v[10:11]
	v_mov_b32_e32 v24, v6
	v_mov_b32_e32 v25, v9
	v_add_u32_e32 v8, v8, v177
	v_mov_b32_e32 v22, v7
	v_pk_mul_f32 v[24:25], v[24:25], v[2:3]
	v_mov_b32_e32 v27, v6
	v_pk_mov_b32 v[28:29], v[2:3], v[10:11] op_sel:[1,0]
	v_mov_b32_e32 v6, v9
	v_pk_mov_b32 v[2:3], v[10:11], v[2:3] op_sel:[1,0]
	v_lshl_add_u32 v13, v8, 3, s4
	v_pk_mul_f32 v[2:3], v[6:7], v[2:3]
	v_pk_fma_f32 v[6:7], v[22:23], v[10:11], v[24:25]
	ds_read_b128 v[8:11], v13
	ds_read_b128 v[22:25], v13 offset:16
	v_pk_fma_f32 v[2:3], v[26:27], v[28:29], v[2:3] neg_lo:[0,0,1] neg_hi:[0,0,1]
	v_pk_mul_f32 v[26:27], v[46:47], v[12:13] op_sel_hi:[1,0]
	v_pk_fma_f32 v[0:1], v[36:37], v[38:39], v[0:1] neg_lo:[0,0,1] neg_hi:[0,0,1]
	v_pk_mul_f32 v[18:19], v[18:19], v[26:27]
	v_pk_mul_f32 v[26:27], v[150:151], v[12:13] op_sel_hi:[1,0]
	s_waitcnt lgkmcnt(0)
	v_mov_b32_e32 v28, v8
	v_pk_mul_f32 v[20:21], v[20:21], v[26:27]
	v_mov_b32_e32 v29, v11
	v_mov_b32_e32 v27, v10
	v_pk_mul_f32 v[28:29], v[28:29], v[18:19]
	v_mov_b32_e32 v34, v10
	v_mov_b32_e32 v35, v8
	v_pk_mov_b32 v[36:37], v[18:19], v[20:21] op_sel:[1,0]
	v_mov_b32_e32 v8, v11
	v_pk_mov_b32 v[10:11], v[20:21], v[18:19] op_sel:[1,0]
	v_pk_mul_f32 v[18:19], v[48:49], v[12:13] op_sel_hi:[1,0]
	v_pk_mul_f32 v[12:13], v[148:149], v[12:13] op_sel_hi:[1,0]
	v_mov_b32_e32 v26, v9
	v_pk_mul_f32 v[8:9], v[8:9], v[10:11]
	v_pk_mul_f32 v[14:15], v[14:15], v[18:19]
	v_pk_mul_f32 v[16:17], v[16:17], v[12:13]
	v_mov_b32_e32 v12, v22
	v_mov_b32_e32 v13, v25
	v_pk_fma_f32 v[10:11], v[34:35], v[36:37], v[8:9] neg_lo:[0,0,1] neg_hi:[0,0,1]
	v_pk_fma_f32 v[8:9], v[26:27], v[20:21], v[28:29]
	v_pk_mul_f32 v[20:21], v[12:13], v[14:15]
	v_mov_b32_e32 v13, v22
	v_pk_mov_b32 v[26:27], v[14:15], v[16:17] op_sel:[1,0]
	v_mov_b32_e32 v22, v25
	v_pk_mov_b32 v[14:15], v[16:17], v[14:15] op_sel:[1,0]
	v_mov_b32_e32 v18, v23
	v_mov_b32_e32 v19, v24
	v_mov_b32_e32 v12, v24
	v_pk_mul_f32 v[14:15], v[22:23], v[14:15]
	s_nop 0
	v_pk_fma_f32 v[12:13], v[12:13], v[26:27], v[14:15] neg_lo:[0,0,1] neg_hi:[0,0,1]
	v_pk_fma_f32 v[14:15], v[18:19], v[16:17], v[20:21]
	s_and_b64 vcc, exec, s[42:43]
	s_cbranch_vccz .LBB0_832
	s_branch .LBB0_833
